# P0 weight-transpose work split: GEMV workgroups take 10 items per wave (was 11), the other 48 take 20-21 (was 16-17)
# baseline (speedup 1.0000x reference)
.LBB0_59:
.LBB0_60:
	s_and_b64 s[0:1], exec, s[12:13]
	s_cselect_b32 s0, 20, 10
.LBB0_61:
	s_and_b64 s[8:9], s[6:7], s[12:13]
	s_cmpk_lt_i32 s20, 0x780
	s_cselect_b64 s[4:5], -1, 0
	s_and_b64 s[4:5], s[8:9], s[4:5]
	v_cndmask_b32_e64 v0, 0, 1, s[4:5]
	s_nop 0
	v_readfirstlane_b32 s1, v0
	s_add_i32 s1, s0, s1
	s_cmp_lt_i32 s1, 1
	s_cbranch_scc1 .LBB0_93
	s_mulk_i32 s2, 0x2400
	s_add_i32 s4, s2, 0
	s_add_i32 s2, s20, 0x3a80
	s_and_b64 s[8:9], s[8:9], exec
	s_cselect_b32 s2, s2, s20
	s_movk_i32 s10, 0x180
	s_and_b64 s[8:9], exec, s[12:13]
	s_cselect_b32 s8, s10, 0x680
	s_and_b64 s[6:7], s[6:7], exec
	s_cselect_b32 s3, s8, s3
	s_addk_i32 s20, 0x5880
	s_add_u32 s21, s28, 0x12800000
	s_addc_u32 s22, s29, 0
	s_add_u32 s23, s28, 0xa800000
	s_addc_u32 s24, s29, 0
	s_add_u32 s25, s28, 0x9800000
	s_addc_u32 s30, s29, 0
	s_add_u32 s31, s28, 0x8800000
	s_addc_u32 s33, s29, 0
	s_add_u32 s6, s28, 0x8000000
	s_addc_u32 s7, s29, 0
	s_add_u32 s8, s28, 0x7800000
	s_addc_u32 s9, s29, 0
	s_add_u32 s34, s28, 0x7000000
	s_addc_u32 s35, s29, 0
	v_and_b32_e32 v1, 7, v26
	v_lshrrev_b32_e32 v3, 3, v21
	s_add_u32 s28, s28, 0x2800000
	v_and_b32_e32 v0, 0x7c, v27
	v_mov_b32_e32 v57, 0
	v_mul_u32_u24_e32 v4, 0x90, v21
	v_lshlrev_b32_e32 v61, 2, v3
	v_lshlrev_b32_e32 v2, 3, v1
	v_lshl_add_u32 v1, v1, 4, s4
	v_mul_u32_u24_e32 v3, 0x90, v3
	s_mov_b32 s5, 0
	s_addc_u32 s29, s29, 0
	v_lshrrev_b32_e32 v60, 5, v21
	v_lshlrev_b32_e32 v56, 2, v0
	v_add_u32_e32 v62, s4, v4
	v_lshlrev_b32_e32 v58, 1, v2
	v_mov_b32_e32 v59, v57
	v_add_u32_e32 v63, v1, v3
	v_mov_b32_e32 v64, 0xffffff42
	s_mov_b32 s36, 0
	s_branch .LBB0_64
